# attention steady loop: K/V DMA issue moved behind the first three PV MFMAs so the row-max chain and rescale decision start right after the last QK MFMA
# baseline (speedup 1.0000x reference)
.LBB0_1277:
	s_lshl_b32 s18, s23, 1
	v_mfma_f32_32x32x16_bf16 v[112:127], v[188:191], v[156:159], v[238:253]
	v_add_u32_e32 v237, s18, v214
	ds_read_b64_tr_b16 v[192:193], v237 offset:24576
	v_add_f32_e32 v128, v80, v81
	v_add_f32_e32 v128, v82, v128
	v_add_f32_e32 v128, v83, v128
	v_add_f32_e32 v128, v84, v128
	v_add_f32_e32 v128, v85, v128
	v_cvt_pk_bf16_f32 v148, v80, v81
	v_cvt_pk_bf16_f32 v149, v82, v83
	ds_read_b64_tr_b16 v[194:195], v237 offset:25088
	s_waitcnt lgkmcnt(8)
	v_mfma_f32_32x32x16_bf16 v[112:127], v[180:183], v[152:155], v[112:127]
	v_add_f32_e32 v80, v86, v128
	v_add_f32_e32 v80, v87, v80
	v_add_f32_e32 v80, v88, v80
	v_add_f32_e32 v82, v89, v80
	v_cvt_pk_bf16_f32 v150, v84, v85
	v_cvt_pk_bf16_f32 v151, v86, v87
	ds_read_b64_tr_b16 v[80:81], v237 offset:28672
	s_waitcnt lgkmcnt(8)
	v_mfma_f32_32x32x16_bf16 v[112:127], v[172:175], v[144:147], v[112:127]
	v_add_f32_e32 v82, v90, v82
	v_add_f32_e32 v82, v91, v82
	v_add_f32_e32 v82, v92, v82
	v_add_f32_e32 v84, v93, v82
	v_cvt_pk_bf16_f32 v140, v88, v89
	v_cvt_pk_bf16_f32 v141, v90, v91
	ds_read_b64_tr_b16 v[82:83], v237 offset:29184
	s_waitcnt lgkmcnt(8)
	v_mfma_f32_32x32x16_bf16 v[112:127], v[164:167], v[136:139], v[112:127]
	v_add_f32_e32 v84, v94, v84
	v_add_f32_e32 v84, v95, v84
	v_add_f32_e32 v84, v64, v84
	v_add_f32_e32 v86, v65, v84
	v_cvt_pk_bf16_f32 v142, v92, v93
	v_cvt_pk_bf16_f32 v143, v94, v95
	ds_read_b64_tr_b16 v[84:85], v237 offset:32768
	s_waitcnt lgkmcnt(8)
	v_mfma_f32_32x32x16_bf16 v[96:111], v[184:187], v[156:159], v[238:253]
	v_add_f32_e32 v86, v66, v86
	v_add_f32_e32 v86, v67, v86
	v_add_f32_e32 v86, v68, v86
	v_add_f32_e32 v88, v69, v86
	v_cvt_pk_bf16_f32 v132, v64, v65
	v_cvt_pk_bf16_f32 v133, v66, v67
	ds_read_b64_tr_b16 v[86:87], v237 offset:33280
	s_waitcnt lgkmcnt(8)
	v_mfma_f32_32x32x16_bf16 v[96:111], v[176:179], v[152:155], v[96:111]
	v_add_f32_e32 v64, v70, v88
	v_add_f32_e32 v64, v71, v64
	v_add_f32_e32 v64, v72, v64
	v_add_f32_e32 v66, v73, v64
	v_cvt_pk_bf16_f32 v134, v68, v69
	v_cvt_pk_bf16_f32 v135, v70, v71
	ds_read_b64_tr_b16 v[64:65], v237 offset:36864
	s_waitcnt lgkmcnt(8)
	v_mfma_f32_32x32x16_bf16 v[96:111], v[168:171], v[144:147], v[96:111]
	v_add_f32_e32 v66, v74, v66
	v_add_f32_e32 v66, v75, v66
	v_add_f32_e32 v66, v76, v66
	v_add_f32_e32 v68, v77, v66
	v_cvt_pk_bf16_f32 v128, v72, v73
	v_cvt_pk_bf16_f32 v129, v74, v75
	v_max_f32_e32 v69, v112, v113
	v_max3_f32 v69, v69, v114, v115
	v_max3_f32 v69, v69, v116, v117
	v_max3_f32 v69, v69, v118, v119
	ds_read_b64_tr_b16 v[66:67], v237 offset:37376
	s_waitcnt lgkmcnt(8)
	v_mfma_f32_32x32x16_bf16 v[96:111], v[160:163], v[136:139], v[96:111]
	v_add_f32_e32 v68, v78, v68
	v_add_f32_e32 v68, v79, v68
	v_add_f32_e32 v236, v236, v68
	v_cvt_pk_bf16_f32 v130, v76, v77
	v_cvt_pk_bf16_f32 v131, v78, v79
	v_max3_f32 v69, v69, v120, v121
	v_max3_f32 v69, v69, v122, v123
	v_max3_f32 v69, v69, v124, v125
	v_max3_f32 v69, v69, v126, v127
	v_max_f32_e32 v70, v96, v97
	v_max_f32_e32 v71, v104, v105
	v_max3_f32 v70, v70, v98, v99
	v_max3_f32 v71, v71, v106, v107
	v_max3_f32 v70, v70, v100, v101
	v_max3_f32 v71, v71, v108, v109
	v_max3_f32 v70, v70, v102, v103
	v_max3_f32 v71, v71, v110, v111
	v_max3_f32 v68, v69, v70, v71
	v_cmp_lt_f32_e32 vcc, s71, v68
	s_cmp_lg_u64 vcc, 0
	s_cselect_b64 s[50:51], -1, 0
	s_cbranch_vccnz .LBB0_1285
.LBB0_1278:
	ds_read_b64_tr_b16 v[68:69], v237 offset:25600
	ds_read_b64_tr_b16 v[70:71], v237 offset:26112
	s_waitcnt lgkmcnt(8)
	v_mfma_f32_32x32x16_bf16 v[32:47], v[148:151], v[192:195], v[32:47]
	s_add_u32 s30, s98, 0xffffe000
	s_addc_u32 s31, s99, -1
	s_add_i32 s18, s86, s89
	s_nop 0
	s_mov_b32 s23, m0
	s_mov_b32 m0, s18
	s_nop 0
	global_load_lds_dwordx4 v196, s[30:31]
	s_mov_b32 m0, s23
	v_exp_f32_e32 v112, v112
	v_exp_f32_e32 v113, v113
	ds_read_b64_tr_b16 v[72:73], v237 offset:29696
	ds_read_b64_tr_b16 v[74:75], v237 offset:30208
	s_waitcnt lgkmcnt(8)
	v_mfma_f32_32x32x16_bf16 v[48:63], v[148:151], v[80:83], v[48:63]
	s_add_u32 s30, s100, 0xffffc000
	s_addc_u32 s31, s101, -1
	s_lshl_b32 s18, s37, 1
	s_add_i32 s18, s18, s90
	s_mov_b32 s23, m0
	s_mov_b32 m0, s18
	s_nop 0
	global_load_lds_dwordx4 v196, s[30:31]
	s_mov_b32 m0, s23
	v_exp_f32_e32 v114, v114
	v_exp_f32_e32 v115, v115
	ds_read_b64_tr_b16 v[76:77], v237 offset:33792
	ds_read_b64_tr_b16 v[78:79], v237 offset:34304
	s_waitcnt lgkmcnt(8)
	v_mfma_f32_32x32x16_bf16 v[16:31], v[148:151], v[84:87], v[16:31]
	s_add_u32 s30, s100, 0xffffe000
	s_addc_u32 s31, s101, -1
	s_addk_i32 s18, 0x2000
	s_mov_b32 s23, m0
	s_mov_b32 m0, s18
	s_nop 0
	global_load_lds_dwordx4 v196, s[30:31]
	s_mov_b32 m0, s23
	v_exp_f32_e32 v116, v116
	v_exp_f32_e32 v117, v117
	ds_read_b64_tr_b16 v[80:81], v237 offset:37888
	ds_read_b64_tr_b16 v[82:83], v237 offset:38400
	s_waitcnt lgkmcnt(8)
	v_mfma_f32_32x32x16_bf16 v[0:15], v[148:151], v[64:67], v[0:15]
	v_exp_f32_e32 v118, v118
	v_exp_f32_e32 v119, v119
	ds_read_b64_tr_b16 v[64:65], v237 offset:26624
	ds_read_b64_tr_b16 v[66:67], v237 offset:27136
	s_waitcnt lgkmcnt(8)
	v_mfma_f32_32x32x16_bf16 v[32:47], v[140:143], v[68:71], v[32:47]
	v_exp_f32_e32 v120, v120
	v_exp_f32_e32 v121, v121
	ds_read_b64_tr_b16 v[68:69], v237 offset:30720
	ds_read_b64_tr_b16 v[70:71], v237 offset:31232
	s_waitcnt lgkmcnt(8)
	v_mfma_f32_32x32x16_bf16 v[48:63], v[140:143], v[72:75], v[48:63]
	v_exp_f32_e32 v122, v122
	v_exp_f32_e32 v123, v123
	ds_read_b64_tr_b16 v[72:73], v237 offset:34816
	ds_read_b64_tr_b16 v[74:75], v237 offset:35328
	s_waitcnt lgkmcnt(8)
	v_mfma_f32_32x32x16_bf16 v[16:31], v[140:143], v[76:79], v[16:31]
	v_exp_f32_e32 v124, v124
	v_exp_f32_e32 v125, v125
	ds_read_b64_tr_b16 v[76:77], v237 offset:38912
	ds_read_b64_tr_b16 v[78:79], v237 offset:39424
	s_waitcnt lgkmcnt(8)
; #define WAIT_BAR(N) asm volatile("s_waitcnt vmcnt(" #N ") lgkmcnt(0)\n\ts_barrier":::"memory")
;   #define RESC() do{ if(resc){ asm volatile("s_waitcnt lgkmcnt(0)":::"memory"); \
;       _Pragma("unroll") for(int d_=0;d_<4;++d_) _Pragma("unroll") for(int r=0;r<16;++r)o[d_][r]*=wsf[crow(r,hi)]; } }while(0)
;   #define ROT() do{sl_prev=sl_cur;sl_cur=sl_next;sl_next=(sl_next==(NSLOT-1)*SLOTB)?0:sl_next+SLOTB;}while(0)
; template<int THRL> __device__ __forceinline__ void attn_unit(int b,int hc,int qb,const bf16*Q,const bf16*__restrict__ K,const bf16*__restrict__ V,bf16*O,char*shm){
;     ...
;   int t=1;
;     ...
;   for(;t+7<NT;t+=2){
;     STEP(pB0,pB1,pA0,pA1,t,true,true,true);     WAIT_BAR(3); RESC(); ROT();
;     STEP(pA0,pA1,pB0,pB1,t+1,true,true,true);   WAIT_BAR(3); RESC(); ROT();
	v_mfma_f32_32x32x16_bf16 v[0:15], v[140:143], v[80:83], v[0:15]
	v_exp_f32_e32 v126, v126
	v_exp_f32_e32 v127, v127
	ds_read_b64_tr_b16 v[80:81], v237 offset:27648
	ds_read_b64_tr_b16 v[82:83], v237 offset:28160
	s_waitcnt lgkmcnt(8)
	v_mfma_f32_32x32x16_bf16 v[32:47], v[132:135], v[64:67], v[32:47]
	v_exp_f32_e32 v96, v96
	v_exp_f32_e32 v97, v97
	ds_read_b64_tr_b16 v[64:65], v237 offset:31744
	ds_read_b64_tr_b16 v[66:67], v237 offset:32256
	s_waitcnt lgkmcnt(8)
	v_mfma_f32_32x32x16_bf16 v[48:63], v[132:135], v[68:71], v[48:63]
	v_exp_f32_e32 v98, v98
	v_exp_f32_e32 v99, v99
	ds_read_b64_tr_b16 v[68:69], v237 offset:35840
	ds_read_b64_tr_b16 v[70:71], v237 offset:36352
	s_waitcnt lgkmcnt(8)
	v_mfma_f32_32x32x16_bf16 v[16:31], v[132:135], v[72:75], v[16:31]
	v_exp_f32_e32 v100, v100
	v_exp_f32_e32 v101, v101
	ds_read_b64_tr_b16 v[72:73], v237 offset:39936
	ds_read_b64_tr_b16 v[74:75], v237 offset:40448
	s_waitcnt lgkmcnt(8)
	v_mfma_f32_32x32x16_bf16 v[0:15], v[132:135], v[76:79], v[0:15]
	v_exp_f32_e32 v102, v102
	v_exp_f32_e32 v103, v103
	v_add_u32_e32 v76, s37, v213
	ds_read_b128 v[192:195], v76
	ds_read_b128 v[188:191], v76 offset:512
	s_waitcnt lgkmcnt(8)
	v_mfma_f32_32x32x16_bf16 v[32:47], v[128:131], v[80:83], v[32:47]
	v_exp_f32_e32 v104, v104
	v_exp_f32_e32 v105, v105
	ds_read_b128 v[184:187], v76 offset:2048
	ds_read_b128 v[176:179], v76 offset:2560
	s_waitcnt lgkmcnt(8)
	v_mfma_f32_32x32x16_bf16 v[48:63], v[128:131], v[64:67], v[48:63]
	v_exp_f32_e32 v106, v106
	v_exp_f32_e32 v107, v107
	ds_read_b128 v[172:175], v76 offset:4096
	ds_read_b128 v[168:171], v76 offset:4608
	s_waitcnt lgkmcnt(8)
	v_mfma_f32_32x32x16_bf16 v[16:31], v[128:131], v[68:71], v[16:31]
	v_exp_f32_e32 v108, v108
	v_exp_f32_e32 v109, v109
	ds_read_b128 v[164:167], v76 offset:6144
	ds_read_b128 v[160:163], v76 offset:6656
	v_exp_f32_e32 v110, v110
	v_exp_f32_e32 v111, v111
	s_waitcnt lgkmcnt(8)
	v_mfma_f32_32x32x16_bf16 v[0:15], v[128:131], v[72:75], v[0:15]
	s_waitcnt vmcnt(3) lgkmcnt(0)
	s_barrier
	s_andn2_b64 vcc, exec, s[50:51]
	s_cbranch_vccnz .LBB0_1280
	s_waitcnt lgkmcnt(0)
	v_add_u32_e32 v76, s49, v216
	ds_read_b128 v[64:67], v76 offset:96
	ds_read_b128 v[68:71], v76 offset:64
	ds_read_b128 v[72:75], v76 offset:32
	ds_read_b128 v[76:79], v76
	s_waitcnt lgkmcnt(3)
	v_pk_mul_f32 v[44:45], v[44:45], v[64:65]
	s_waitcnt lgkmcnt(2)
	v_pk_mul_f32 v[40:41], v[40:41], v[68:69]
	s_waitcnt lgkmcnt(1)
	v_pk_mul_f32 v[36:37], v[36:37], v[72:73]
	v_pk_mul_f32 v[46:47], v[46:47], v[66:67]
	v_pk_mul_f32 v[42:43], v[42:43], v[70:71]
	v_pk_mul_f32 v[38:39], v[38:39], v[74:75]
	s_waitcnt lgkmcnt(0)
	v_pk_mul_f32 v[34:35], v[34:35], v[78:79]
	v_pk_mul_f32 v[32:33], v[32:33], v[76:77]
	v_pk_mul_f32 v[60:61], v[60:61], v[64:65]
	v_pk_mul_f32 v[56:57], v[56:57], v[68:69]
	v_pk_mul_f32 v[52:53], v[52:53], v[72:73]
	v_pk_mul_f32 v[62:63], v[62:63], v[66:67]
	v_pk_mul_f32 v[58:59], v[58:59], v[70:71]
	v_pk_mul_f32 v[54:55], v[54:55], v[74:75]
	v_pk_mul_f32 v[50:51], v[50:51], v[78:79]
	v_pk_mul_f32 v[48:49], v[48:49], v[76:77]
	v_pk_mul_f32 v[28:29], v[28:29], v[64:65]
	v_pk_mul_f32 v[24:25], v[24:25], v[68:69]
	v_pk_mul_f32 v[20:21], v[20:21], v[72:73]
	v_pk_mul_f32 v[30:31], v[30:31], v[66:67]
	v_pk_mul_f32 v[26:27], v[26:27], v[70:71]
	v_pk_mul_f32 v[22:23], v[22:23], v[74:75]
	v_pk_mul_f32 v[18:19], v[18:19], v[78:79]
	v_pk_mul_f32 v[16:17], v[16:17], v[76:77]
	v_pk_mul_f32 v[12:13], v[12:13], v[64:65]
	v_pk_mul_f32 v[8:9], v[8:9], v[68:69]
	v_pk_mul_f32 v[4:5], v[4:5], v[72:73]
	v_pk_mul_f32 v[14:15], v[14:15], v[66:67]
	v_pk_mul_f32 v[10:11], v[10:11], v[70:71]
	v_pk_mul_f32 v[6:7], v[6:7], v[74:75]
	v_pk_mul_f32 v[2:3], v[2:3], v[78:79]
	v_pk_mul_f32 v[0:1], v[0:1], v[76:77]
.LBB0_1280:
	s_add_i32 s18, s37, 0x2000
	s_lshl_b32 s23, s86, 1
	v_mfma_f32_32x32x16_bf16 v[80:95], v[192:195], v[156:159], v[238:253]
	v_add_u32_e32 v237, s23, v214
	ds_read_b64_tr_b16 v[180:181], v237 offset:24576
	s_cmpk_lg_i32 s37, 0x4000
	s_cselect_b32 s86, s18, 0
	v_add_f32_e32 v128, v112, v113
	v_add_f32_e32 v128, v114, v128
	v_add_f32_e32 v128, v115, v128
	v_add_f32_e32 v128, v116, v128
	v_add_f32_e32 v128, v117, v128
	v_cvt_pk_bf16_f32 v148, v112, v113
	v_cvt_pk_bf16_f32 v149, v114, v115
	ds_read_b64_tr_b16 v[182:183], v237 offset:25088
	s_waitcnt lgkmcnt(8)
	v_mfma_f32_32x32x16_bf16 v[80:95], v[184:187], v[152:155], v[80:95]
	v_add_f32_e32 v112, v118, v128
	v_add_f32_e32 v112, v119, v112
	v_add_f32_e32 v112, v120, v112
	v_add_f32_e32 v114, v121, v112
	v_cvt_pk_bf16_f32 v150, v116, v117
	v_cvt_pk_bf16_f32 v151, v118, v119
	ds_read_b64_tr_b16 v[112:113], v237 offset:28672
	s_waitcnt lgkmcnt(8)
	v_mfma_f32_32x32x16_bf16 v[80:95], v[172:175], v[144:147], v[80:95]
	v_add_f32_e32 v114, v122, v114
	v_add_f32_e32 v114, v123, v114
	v_add_f32_e32 v114, v124, v114
	v_add_f32_e32 v116, v125, v114
	v_cvt_pk_bf16_f32 v140, v120, v121
	v_cvt_pk_bf16_f32 v141, v122, v123
	ds_read_b64_tr_b16 v[114:115], v237 offset:29184
	s_waitcnt lgkmcnt(8)
	v_mfma_f32_32x32x16_bf16 v[80:95], v[164:167], v[136:139], v[80:95]
	v_add_f32_e32 v116, v126, v116
	v_add_f32_e32 v116, v127, v116
	v_add_f32_e32 v116, v96, v116
	v_add_f32_e32 v118, v97, v116
	v_cvt_pk_bf16_f32 v142, v124, v125
	v_cvt_pk_bf16_f32 v143, v126, v127
	ds_read_b64_tr_b16 v[116:117], v237 offset:32768
	s_waitcnt lgkmcnt(8)
	v_mfma_f32_32x32x16_bf16 v[64:79], v[188:191], v[156:159], v[238:253]
	v_add_f32_e32 v118, v98, v118
	v_add_f32_e32 v118, v99, v118
	v_add_f32_e32 v118, v100, v118
	v_add_f32_e32 v120, v101, v118
	v_cvt_pk_bf16_f32 v132, v96, v97
	v_cvt_pk_bf16_f32 v133, v98, v99
	ds_read_b64_tr_b16 v[118:119], v237 offset:33280
	s_waitcnt lgkmcnt(8)
	v_mfma_f32_32x32x16_bf16 v[64:79], v[176:179], v[152:155], v[64:79]
	v_add_f32_e32 v96, v102, v120
	v_add_f32_e32 v96, v103, v96
	v_add_f32_e32 v96, v104, v96
	v_add_f32_e32 v98, v105, v96
	v_cvt_pk_bf16_f32 v134, v100, v101
	v_cvt_pk_bf16_f32 v135, v102, v103
	ds_read_b64_tr_b16 v[96:97], v237 offset:36864
	s_waitcnt lgkmcnt(8)
	v_mfma_f32_32x32x16_bf16 v[64:79], v[168:171], v[144:147], v[64:79]
	v_add_f32_e32 v98, v106, v98
	v_add_f32_e32 v98, v107, v98
	v_add_f32_e32 v98, v108, v98
	v_add_f32_e32 v100, v109, v98
	v_cvt_pk_bf16_f32 v128, v104, v105
	v_cvt_pk_bf16_f32 v129, v106, v107
	v_max_f32_e32 v101, v80, v81
	v_max3_f32 v101, v101, v82, v83
	v_max3_f32 v101, v101, v84, v85
	v_max3_f32 v101, v101, v86, v87
	ds_read_b64_tr_b16 v[98:99], v237 offset:37376
	s_waitcnt lgkmcnt(8)
	v_mfma_f32_32x32x16_bf16 v[64:79], v[160:163], v[136:139], v[64:79]
	v_add_f32_e32 v100, v110, v100
	v_add_f32_e32 v100, v111, v100
	v_add_f32_e32 v236, v236, v100
	v_cvt_pk_bf16_f32 v130, v108, v109
	v_cvt_pk_bf16_f32 v131, v110, v111
	v_max3_f32 v101, v101, v88, v89
	v_max3_f32 v101, v101, v90, v91
	v_max3_f32 v101, v101, v92, v93
	v_max3_f32 v101, v101, v94, v95
	v_max_f32_e32 v102, v64, v65
	v_max_f32_e32 v103, v72, v73
	v_max3_f32 v102, v102, v66, v67
	v_max3_f32 v103, v103, v74, v75
	v_max3_f32 v102, v102, v68, v69
	v_max3_f32 v103, v103, v76, v77
	v_max3_f32 v102, v102, v70, v71
	v_max3_f32 v103, v103, v78, v79
	v_max3_f32 v100, v101, v102, v103
	v_cmp_lt_f32_e32 vcc, s71, v100
	s_cmp_lg_u64 vcc, 0
	s_cselect_b64 s[50:51], -1, 0
	s_cbranch_vccnz .LBB0_1288
; #define WAIT_BAR(N) asm volatile("s_waitcnt vmcnt(" #N ") lgkmcnt(0)\n\ts_barrier":::"memory")
;   #define RESC() do{ if(resc){ asm volatile("s_waitcnt lgkmcnt(0)":::"memory"); \
;       _Pragma("unroll") for(int d_=0;d_<4;++d_) _Pragma("unroll") for(int r=0;r<16;++r)o[d_][r]*=wsf[crow(r,hi)]; } }while(0)
;   #define ROT() do{sl_prev=sl_cur;sl_cur=sl_next;sl_next=(sl_next==(NSLOT-1)*SLOTB)?0:sl_next+SLOTB;}while(0)
; template<int THRL> __device__ __forceinline__ void attn_unit(int b,int hc,int qb,const bf16*Q,const bf16*__restrict__ K,const bf16*__restrict__ V,bf16*O,char*shm){
;     ...
;   int t=1;
;     ...
;   for(;t+7<NT;t+=2){
;     STEP(pB0,pB1,pA0,pA1,t,true,true,true);     WAIT_BAR(3); RESC(); ROT();
;     STEP(pA0,pA1,pB0,pB1,t+1,true,true,true);   WAIT_BAR(3); RESC(); ROT();
.LBB0_1281:
	ds_read_b64_tr_b16 v[100:101], v237 offset:25600
	ds_read_b64_tr_b16 v[102:103], v237 offset:26112
	s_waitcnt lgkmcnt(8)
	v_mfma_f32_32x32x16_bf16 v[32:47], v[148:151], v[180:183], v[32:47]
	s_add_i32 s18, s37, s89
	s_mov_b32 s23, m0
	s_mov_b32 m0, s18
	s_nop 0
	global_load_lds_dwordx4 v196, s[98:99]
	s_mov_b32 m0, s23
	v_exp_f32_e32 v80, v80
	v_exp_f32_e32 v81, v81
	ds_read_b64_tr_b16 v[104:105], v237 offset:29696
	ds_read_b64_tr_b16 v[106:107], v237 offset:30208
	s_waitcnt lgkmcnt(8)
	v_mfma_f32_32x32x16_bf16 v[48:63], v[148:151], v[112:115], v[48:63]
	s_lshl_b32 s18, s86, 1
	s_add_i32 s18, s18, s90
	s_mov_b32 s23, m0
	s_mov_b32 m0, s18
	s_nop 0
	global_load_lds_dwordx4 v196, s[100:101]
	s_mov_b32 m0, s23
	v_exp_f32_e32 v82, v82
	v_exp_f32_e32 v83, v83
	ds_read_b64_tr_b16 v[108:109], v237 offset:33792
	ds_read_b64_tr_b16 v[110:111], v237 offset:34304
	s_waitcnt lgkmcnt(8)
	v_mfma_f32_32x32x16_bf16 v[16:31], v[148:151], v[116:119], v[16:31]
	s_add_u32 s30, s100, 0x2000
	s_addc_u32 s31, s101, 0
	s_addk_i32 s18, 0x2000
	s_mov_b32 s23, m0
	s_mov_b32 m0, s18
	s_nop 0
	global_load_lds_dwordx4 v196, s[30:31]
	s_mov_b32 m0, s23
	v_exp_f32_e32 v84, v84
	v_exp_f32_e32 v85, v85
	ds_read_b64_tr_b16 v[112:113], v237 offset:37888
	ds_read_b64_tr_b16 v[114:115], v237 offset:38400
	s_waitcnt lgkmcnt(8)
	v_mfma_f32_32x32x16_bf16 v[0:15], v[148:151], v[96:99], v[0:15]
	v_exp_f32_e32 v86, v86
	v_exp_f32_e32 v87, v87
	ds_read_b64_tr_b16 v[96:97], v237 offset:26624
	ds_read_b64_tr_b16 v[98:99], v237 offset:27136
	s_waitcnt lgkmcnt(8)
	v_mfma_f32_32x32x16_bf16 v[32:47], v[140:143], v[100:103], v[32:47]
	v_exp_f32_e32 v88, v88
	v_exp_f32_e32 v89, v89
	ds_read_b64_tr_b16 v[100:101], v237 offset:30720
	ds_read_b64_tr_b16 v[102:103], v237 offset:31232
	s_waitcnt lgkmcnt(8)
	v_mfma_f32_32x32x16_bf16 v[48:63], v[140:143], v[104:107], v[48:63]
	v_exp_f32_e32 v90, v90
	v_exp_f32_e32 v91, v91
	ds_read_b64_tr_b16 v[104:105], v237 offset:34816
	ds_read_b64_tr_b16 v[106:107], v237 offset:35328
	s_waitcnt lgkmcnt(8)
	v_mfma_f32_32x32x16_bf16 v[16:31], v[140:143], v[108:111], v[16:31]
	v_exp_f32_e32 v92, v92
	v_exp_f32_e32 v93, v93
	ds_read_b64_tr_b16 v[108:109], v237 offset:38912
	ds_read_b64_tr_b16 v[110:111], v237 offset:39424
	s_waitcnt lgkmcnt(8)
	v_mfma_f32_32x32x16_bf16 v[0:15], v[140:143], v[112:115], v[0:15]
	v_exp_f32_e32 v94, v94
	v_exp_f32_e32 v95, v95
	ds_read_b64_tr_b16 v[112:113], v237 offset:27648
	ds_read_b64_tr_b16 v[114:115], v237 offset:28160
	s_waitcnt lgkmcnt(8)
	v_mfma_f32_32x32x16_bf16 v[32:47], v[132:135], v[96:99], v[32:47]
	v_exp_f32_e32 v64, v64
	v_exp_f32_e32 v65, v65
	ds_read_b64_tr_b16 v[96:97], v237 offset:31744
	ds_read_b64_tr_b16 v[98:99], v237 offset:32256
	s_waitcnt lgkmcnt(8)
	v_mfma_f32_32x32x16_bf16 v[48:63], v[132:135], v[100:103], v[48:63]
	v_exp_f32_e32 v66, v66
	v_exp_f32_e32 v67, v67
	ds_read_b64_tr_b16 v[100:101], v237 offset:35840
	ds_read_b64_tr_b16 v[102:103], v237 offset:36352
	s_waitcnt lgkmcnt(8)
	v_mfma_f32_32x32x16_bf16 v[16:31], v[132:135], v[104:107], v[16:31]
	v_exp_f32_e32 v68, v68
	v_exp_f32_e32 v69, v69
	ds_read_b64_tr_b16 v[104:105], v237 offset:39936
	ds_read_b64_tr_b16 v[106:107], v237 offset:40448
	s_waitcnt lgkmcnt(8)
	v_mfma_f32_32x32x16_bf16 v[0:15], v[132:135], v[108:111], v[0:15]
	v_exp_f32_e32 v70, v70
	v_exp_f32_e32 v71, v71
	v_add_u32_e32 v108, s86, v213
	ds_read_b128 v[188:191], v108
	ds_read_b128 v[184:187], v108 offset:512
	s_waitcnt lgkmcnt(8)
	v_mfma_f32_32x32x16_bf16 v[32:47], v[128:131], v[112:115], v[32:47]
	v_exp_f32_e32 v72, v72
	v_exp_f32_e32 v73, v73
	ds_read_b128 v[180:183], v108 offset:2048
	ds_read_b128 v[176:179], v108 offset:2560
	s_waitcnt lgkmcnt(8)
	v_mfma_f32_32x32x16_bf16 v[48:63], v[128:131], v[96:99], v[48:63]
	v_exp_f32_e32 v74, v74
	v_exp_f32_e32 v75, v75
	ds_read_b128 v[172:175], v108 offset:4096
	ds_read_b128 v[168:171], v108 offset:4608
	s_waitcnt lgkmcnt(8)
	v_mfma_f32_32x32x16_bf16 v[16:31], v[128:131], v[100:103], v[16:31]
	v_exp_f32_e32 v76, v76
	v_exp_f32_e32 v77, v77
	ds_read_b128 v[164:167], v108 offset:6144
	ds_read_b128 v[160:163], v108 offset:6656
	v_exp_f32_e32 v78, v78
	v_exp_f32_e32 v79, v79
	s_waitcnt lgkmcnt(8)
	v_mfma_f32_32x32x16_bf16 v[0:15], v[128:131], v[104:107], v[0:15]
	s_waitcnt vmcnt(3) lgkmcnt(0)
	s_barrier
	s_andn2_b64 vcc, exec, s[50:51]
	s_cbranch_vccnz .LBB0_1283
	s_waitcnt lgkmcnt(0)
	v_add_u32_e32 v108, s49, v216
	ds_read_b128 v[96:99], v108 offset:96
	ds_read_b128 v[100:103], v108 offset:64
	ds_read_b128 v[104:107], v108 offset:32
	ds_read_b128 v[108:111], v108
	s_waitcnt lgkmcnt(3)
	v_pk_mul_f32 v[44:45], v[44:45], v[96:97]
	s_waitcnt lgkmcnt(2)
	v_pk_mul_f32 v[40:41], v[40:41], v[100:101]
	s_waitcnt lgkmcnt(1)
	v_pk_mul_f32 v[36:37], v[36:37], v[104:105]
	v_pk_mul_f32 v[46:47], v[46:47], v[98:99]
	v_pk_mul_f32 v[42:43], v[42:43], v[102:103]
	v_pk_mul_f32 v[38:39], v[38:39], v[106:107]
	s_waitcnt lgkmcnt(0)
	v_pk_mul_f32 v[34:35], v[34:35], v[110:111]
	v_pk_mul_f32 v[32:33], v[32:33], v[108:109]
	v_pk_mul_f32 v[60:61], v[60:61], v[96:97]
	v_pk_mul_f32 v[56:57], v[56:57], v[100:101]
	v_pk_mul_f32 v[52:53], v[52:53], v[104:105]
	v_pk_mul_f32 v[62:63], v[62:63], v[98:99]
	v_pk_mul_f32 v[58:59], v[58:59], v[102:103]
	v_pk_mul_f32 v[54:55], v[54:55], v[106:107]
	v_pk_mul_f32 v[50:51], v[50:51], v[110:111]
	v_pk_mul_f32 v[48:49], v[48:49], v[108:109]
	v_pk_mul_f32 v[28:29], v[28:29], v[96:97]
	v_pk_mul_f32 v[24:25], v[24:25], v[100:101]
	v_pk_mul_f32 v[20:21], v[20:21], v[104:105]
	v_pk_mul_f32 v[30:31], v[30:31], v[98:99]
	v_pk_mul_f32 v[26:27], v[26:27], v[102:103]
	v_pk_mul_f32 v[22:23], v[22:23], v[106:107]
	v_pk_mul_f32 v[18:19], v[18:19], v[110:111]
	v_pk_mul_f32 v[16:17], v[16:17], v[108:109]
	v_pk_mul_f32 v[12:13], v[12:13], v[96:97]
	v_pk_mul_f32 v[8:9], v[8:9], v[100:101]
	v_pk_mul_f32 v[4:5], v[4:5], v[104:105]
	v_pk_mul_f32 v[14:15], v[14:15], v[98:99]
	v_pk_mul_f32 v[10:11], v[10:11], v[102:103]
	v_pk_mul_f32 v[6:7], v[6:7], v[106:107]
	v_pk_mul_f32 v[2:3], v[2:3], v[110:111]
	v_pk_mul_f32 v[0:1], v[0:1], v[108:109]
